# index score loop: key blocks prefetched two iterations ahead (second landing set, counted vmcnt) instead of draining a one-ahead prefetch every iteration
# speedup vs baseline: 1.0050x; 1.0031x over previous
; DI float bf2f(unsigned short h) { return __uint_as_float(((unsigned)h) << 16); }
; DI void index_unit(Frame& F, int b, int t0) {
;     ...
;     const int rg = r >> 3, rhh = (r >> 2) & 1, rc = r & 3, a_tq = 2 * rhh + (rg >> 1), a_hd = 4 * (rg & 1) + rc;
;     bf16x8 qa[2][4]; float wv[2][16];
; #pragma unroll
;     for (int mt = 0; mt < 2; ++mt) {
;         const bf16* qp = H0 + (size_t)(b * SEQ + t0 + 4 * mt + a_tq) * EVEN_LD + C_QI + a_hd * 64 + 8 * hf;
; #pragma unroll
;         for (int st = 0; st < 4; ++st) qa[mt][st] = *(const bf16x8*)(qp + 16 * st);
; #pragma unroll
;         for (int q = 0; q < 2; ++q) {
;             const bf16* wp = H0 + (size_t)(b * SEQ + t0 + 4 * mt + 2 * hf + q) * EVEN_LD + C_WI;
;             const u32x4 wr = *(const u32x4*)wp;
; #pragma unroll
;             for (int k = 0; k < 4; ++k) { const unsigned u = wr[k]; wv[mt][8 * q + 2 * k] = bf2f((unsigned short)(u & 0xffff)) * 0.04419417382415922f; wv[mt][8 * q + 2 * k + 1] = bf2f((unsigned short)(u >> 16)) * 0.04419417382415922f; }
;         }
;     }
;     const int nkt = (t0 + 8 + 31) >> 5;
;     if (t0 + 8 > 256) for (int _r22 = 0; _r22 < (PROBE_PHASE == 22 ? 2 : 1); ++_r22) {
;         bf16x8 kb[4], kn[4];
;         { const bf16* kp = H0 + (size_t)(b * SEQ + 32 * w + r) * EVEN_LD + C_KI + 8 * hf;
;           if (w < nkt) {
; #pragma unroll
;               for (int st = 0; st < 4; ++st) kb[st] = *(const bf16x8*)(kp + 16 * st); } }
;         for (int kt = w; kt < nkt; kt += NWAVES) {
;             const int s = 32 * kt + r;
;             if (kt + NWAVES < nkt) { const bf16* kp = H0 + (size_t)(b * SEQ + s + 32 * NWAVES) * EVEN_LD + C_KI + 8 * hf;
; #pragma unroll
;                 for (int st = 0; st < 4; ++st) kn[st] = *(const bf16x8*)(kp + 16 * st); }
.LBB0_209:
	s_bitcmp0_b32 s30, 0
	s_cselect_b32 s1, s84, s29
	s_add_i32 s1, s1, s0
	s_cmpk_gt_i32 s1, 0x7ff
	s_cbranch_scc1 .LBB0_208
	s_lshl_b32 s0, s1, 1
	s_and_b32 s0, s0, -8
	s_lshl_b32 s1, s1, 12
	s_sub_i32 s4, 0xff8, s0
	s_and_b32 s31, s1, 0x3000
	s_cmpk_lt_u32 s4, 0xf9
	s_waitcnt vmcnt(0) lgkmcnt(0)
	s_barrier
	s_cbranch_scc1 .LBB0_216
	s_sub_i32 s0, 0x1018, s0
	s_lshr_b32 s5, s0, 5
	s_cmp_ge_u32 s82, s5
	s_cbranch_scc1 .LBB0_216
	s_add_i32 s6, s4, s31
	v_or_b32_e32 v2, s6, v90
	v_mov_b64_e32 v[0:1], s[24:25]
	v_mad_u64_u32 v[2:3], s[0:1], v2, s19, v[0:1]
	v_mov_b32_e32 v89, v81
	v_lshl_add_u64 v[2:3], v[2:3], 0, v[88:89]
	v_lshlrev_b32_e32 v80, 1, v82
	v_lshl_add_u64 v[2:3], v[2:3], 0, v[80:81]
	s_mov_b64 s[2:3], 0x3000
	v_lshl_add_u64 v[4:5], v[2:3], 0, s[2:3]
	v_add_co_u32_e32 v2, vcc, 0x3000, v2
	v_or_b32_e32 v6, s6, v91
	s_nop 0
	v_addc_co_u32_e32 v3, vcc, 0, v3, vcc
	global_load_dwordx4 v[16:19], v[2:3], off
	global_load_dwordx4 v[20:23], v[4:5], off offset:32
	global_load_dwordx4 v[24:27], v[4:5], off offset:64
	global_load_dwordx4 v[28:31], v[4:5], off offset:96
	v_mad_i64_i32 v[2:3], s[0:1], v6, s19, v[0:1]
	v_add_co_u32_e32 v2, vcc, 0x3000, v2
	v_or_b32_e32 v6, 1, v6
	s_nop 0
	v_addc_co_u32_e32 v3, vcc, 0, v3, vcc
	global_load_dwordx4 v[2:5], v[2:3], off offset:1152
	v_mad_i64_i32 v[6:7], s[0:1], v6, s19, v[0:1]
	v_add_co_u32_e32 v6, vcc, 0x3000, v6
	s_or_b32 s6, s6, 4
	s_nop 0
	v_addc_co_u32_e32 v7, vcc, 0, v7, vcc
	v_or_b32_e32 v10, s6, v90
	global_load_dwordx4 v[6:9], v[6:7], off offset:1152
	v_mad_u64_u32 v[10:11], s[0:1], v10, s19, v[0:1]
	v_lshl_add_u64 v[10:11], v[10:11], 0, v[88:89]
	v_lshl_add_u64 v[10:11], v[10:11], 0, v[80:81]
	v_lshl_add_u64 v[12:13], v[10:11], 0, s[2:3]
	v_add_co_u32_e32 v10, vcc, 0x3000, v10
	v_or_b32_e32 v14, s6, v91
	s_nop 0
	v_addc_co_u32_e32 v11, vcc, 0, v11, vcc
	global_load_dwordx4 v[32:35], v[10:11], off
	global_load_dwordx4 v[36:39], v[12:13], off offset:32
	global_load_dwordx4 v[40:43], v[12:13], off offset:64
	global_load_dwordx4 v[44:47], v[12:13], off offset:96
	v_mad_i64_i32 v[10:11], s[0:1], v14, s19, v[0:1]
	v_add_co_u32_e32 v10, vcc, 0x3000, v10
	v_or_b32_e32 v14, 1, v14
	s_nop 0
	v_addc_co_u32_e32 v11, vcc, 0, v11, vcc
	global_load_dwordx4 v[10:13], v[10:11], off offset:1152
	v_mad_i64_i32 v[14:15], s[0:1], v14, s19, v[0:1]
	v_add_co_u32_e32 v14, vcc, 0x3000, v14
	v_readlane_b32 s0, v230, 46
	s_nop 0
	v_addc_co_u32_e32 v15, vcc, 0, v15, vcc
	global_load_dwordx4 v[48:51], v[14:15], off offset:1152
	s_add_i32 s0, s0, s31
	v_or_b32_e32 v195, s4, v91
	v_or_b32_e32 v197, s4, v92
	v_or_b32_e32 v196, 1, v195
	v_or_b32_e32 v198, 1, v197
	s_add_i32 s6, s31, 0x100
	v_mov_b32_e32 v199, v162
	v_mov_b32_e32 v200, v161
	s_mov_b32 s7, s82
	s_waitcnt vmcnt(7)
	v_lshlrev_b32_e32 v14, 16, v2
	v_and_b32_e32 v2, 0xffff0000, v2
	v_mul_f32_e32 v164, 0x3d3504f3, v2
	v_lshlrev_b32_e32 v2, 16, v3
	v_mul_f32_e32 v165, 0x3d3504f3, v2
	v_and_b32_e32 v2, 0xffff0000, v3
	v_mul_f32_e32 v166, 0x3d3504f3, v2
	v_lshlrev_b32_e32 v2, 16, v4
	v_mul_f32_e32 v167, 0x3d3504f3, v2
	v_and_b32_e32 v2, 0xffff0000, v4
	v_mul_f32_e32 v168, 0x3d3504f3, v2
	v_lshlrev_b32_e32 v2, 16, v5
	v_mul_f32_e32 v169, 0x3d3504f3, v2
	v_and_b32_e32 v2, 0xffff0000, v5
	v_mul_f32_e32 v170, 0x3d3504f3, v2
	s_waitcnt vmcnt(6)
	v_lshlrev_b32_e32 v2, 16, v6
	v_mul_f32_e32 v171, 0x3d3504f3, v2
	v_and_b32_e32 v2, 0xffff0000, v6
	v_mul_f32_e32 v172, 0x3d3504f3, v2
	v_lshlrev_b32_e32 v2, 16, v7
	v_mul_f32_e32 v173, 0x3d3504f3, v2
	v_and_b32_e32 v2, 0xffff0000, v7
	v_mul_f32_e32 v174, 0x3d3504f3, v2
	v_lshlrev_b32_e32 v2, 16, v8
	v_mul_f32_e32 v175, 0x3d3504f3, v2
	v_and_b32_e32 v2, 0xffff0000, v8
	v_mul_f32_e32 v176, 0x3d3504f3, v2
	v_lshlrev_b32_e32 v2, 16, v9
	v_mul_f32_e32 v177, 0x3d3504f3, v2
	v_and_b32_e32 v2, 0xffff0000, v9
	v_mul_f32_e32 v178, 0x3d3504f3, v2
	s_waitcnt vmcnt(1)
	v_lshlrev_b32_e32 v2, 16, v10
	v_mul_f32_e32 v179, 0x3d3504f3, v2
	v_and_b32_e32 v2, 0xffff0000, v10
	v_mul_f32_e32 v180, 0x3d3504f3, v2
	v_lshlrev_b32_e32 v2, 16, v11
	v_mul_f32_e32 v181, 0x3d3504f3, v2
	v_and_b32_e32 v2, 0xffff0000, v11
	v_mul_f32_e32 v182, 0x3d3504f3, v2
	v_lshlrev_b32_e32 v2, 16, v12
	v_mul_f32_e32 v183, 0x3d3504f3, v2
	v_and_b32_e32 v2, 0xffff0000, v12
	v_mul_f32_e32 v184, 0x3d3504f3, v2
	v_lshlrev_b32_e32 v2, 16, v13
	v_mul_f32_e32 v185, 0x3d3504f3, v2
	v_and_b32_e32 v2, 0xffff0000, v13
	v_mul_f32_e32 v186, 0x3d3504f3, v2
	s_waitcnt vmcnt(0)
	v_lshlrev_b32_e32 v2, 16, v48
	v_mul_f32_e32 v187, 0x3d3504f3, v2
	v_and_b32_e32 v2, 0xffff0000, v48
	v_mul_f32_e32 v188, 0x3d3504f3, v2
	v_lshlrev_b32_e32 v2, 16, v49
	v_mul_f32_e32 v189, 0x3d3504f3, v2
	v_and_b32_e32 v2, 0xffff0000, v49
	v_mul_f32_e32 v190, 0x3d3504f3, v2
	v_lshlrev_b32_e32 v2, 16, v50
	v_mul_f32_e32 v191, 0x3d3504f3, v2
	v_and_b32_e32 v2, 0xffff0000, v50
	v_mul_f32_e32 v192, 0x3d3504f3, v2
	v_lshlrev_b32_e32 v2, 16, v51
	v_mul_f32_e32 v193, 0x3d3504f3, v2
	v_and_b32_e32 v2, 0xffff0000, v51
	v_mul_f32_e32 v194, 0x3d3504f3, v2
	v_or_b32_e32 v2, s0, v85
	v_mad_u64_u32 v[0:1], s[0:1], v2, s19, v[0:1]
	v_lshl_add_u64 v[0:1], v[0:1], 0, v[80:81]
	v_lshl_add_u64 v[2:3], v[0:1], 0, s[10:11]
	v_add_co_u32_e32 v0, vcc, 0x3000, v0
	v_mul_f32_e32 v89, 0x3d3504f3, v14
	s_nop 0
	v_addc_co_u32_e32 v1, vcc, 0, v1, vcc
	global_load_dwordx4 v[60:63], v[0:1], off offset:1024
	global_load_dwordx4 v[56:59], v[2:3], off offset:32
	global_load_dwordx4 v[52:55], v[2:3], off offset:64
	global_load_dwordx4 v[48:51], v[2:3], off offset:96
	s_mov_b32 s100, 0
	s_add_i32 s98, s7, 8
	s_cmp_ge_u32 s98, s5
	s_cbranch_scc1 .Lidx_p0
	v_add_u32_e32 v2, s6, v200
	v_mov_b64_e32 v[0:1], s[24:25]
	v_mad_i64_i32 v[0:1], s[8:9], v2, s19, v[0:1]
	v_lshl_add_u64 v[0:1], v[0:1], 0, v[80:81]
	v_lshl_add_u64 v[2:3], v[0:1], 0, s[10:11]
	v_add_co_u32_e32 v0, vcc, 0x3000, v0
	s_nop 1
	v_addc_co_u32_e32 v1, vcc, 0, v1, vcc
	global_load_dwordx4 v[232:235], v[2:3], off offset:32
	global_load_dwordx4 v[240:243], v[2:3], off offset:64
	global_load_dwordx4 v[236:239], v[0:1], off offset:1024
	global_load_dwordx4 v[244:247], v[2:3], off offset:96
	s_waitcnt vmcnt(4)
	s_branch .LBB0_214
; #define MFMA32(a, b, c) __builtin_amdgcn_mfma_f32_32x32x16_bf16((a), (b), (c), 0, 0, 0)
; DI void index_unit(Frame& F, int b, int t0) {
;     ...
; #pragma unroll
;             for (int mt = 0; mt < 2; ++mt) {
;                 f32x16 x;
; #pragma unroll
;                 for (int i = 0; i < 16; ++i) x[i] = 0.f;
; #pragma unroll
;                 for (int st = 0; st < 4; ++st) x = MFMA32(qa[mt][st], kb[st], x);
;                 float s0v = 0.f, s1v = 0.f;
; #pragma unroll
;                 for (int i = 0; i < 8; ++i) { s0v += wv[mt][i] * fmaxf(x[i], 0.f); s1v += wv[mt][8 + i] * fmaxf(x[8 + i], 0.f); }
;                 const int tq0 = 4 * mt + 2 * hf;
;                 sc[tq0 * 4096 + s] = (s <= t0 + tq0) ? (s0v + 0.f) : -1e30f;
;                 sc[(tq0 + 1) * 4096 + s] = (s <= t0 + tq0 + 1) ? (s1v + 0.f) : -1e30f;
;             }
; #pragma unroll
;             for (int st = 0; st < 4; ++st) kb[st] = kn[st];
;         }
.Lidx_p0:
	s_waitcnt vmcnt(0)
	s_branch .LBB0_214
.Lidx_nopf:
.LBB0_213:
	v_mfma_f32_32x32x16_bf16 v[0:15], v[16:19], v[60:63], 0
	v_cmp_le_i32_e32 vcc, v200, v195
	v_mfma_f32_32x32x16_bf16 v[0:15], v[20:23], v[56:59], v[0:15]
	v_mfma_f32_32x32x16_bf16 v[0:15], v[24:27], v[52:55], v[0:15]
	v_mfma_f32_32x32x16_bf16 v[0:15], v[28:31], v[48:51], v[0:15]
	s_nop 11
	v_max_f32_e32 v0, 0, v0
	v_fma_f32 v0, v89, v0, 0
	v_max_f32_e32 v1, 0, v1
	v_max_f32_e32 v8, 0, v8
	v_fmac_f32_e32 v0, v164, v1
	v_fma_f32 v8, v171, v8, 0
	v_max_f32_e32 v1, 0, v9
	v_fmac_f32_e32 v8, v172, v1
	v_max_f32_e32 v1, 0, v2
	v_fmac_f32_e32 v0, v165, v1
	v_max_f32_e32 v1, 0, v10
	v_fmac_f32_e32 v8, v173, v1
	v_max_f32_e32 v1, 0, v3
	v_fmac_f32_e32 v0, v166, v1
	v_max_f32_e32 v1, 0, v11
	v_fmac_f32_e32 v8, v174, v1
	v_max_f32_e32 v1, 0, v4
	v_fmac_f32_e32 v0, v167, v1
	v_max_f32_e32 v1, 0, v12
	v_fmac_f32_e32 v8, v175, v1
	v_max_f32_e32 v1, 0, v5
	v_fmac_f32_e32 v0, v168, v1
	v_max_f32_e32 v1, 0, v13
	v_fmac_f32_e32 v8, v176, v1
	v_max_f32_e32 v1, 0, v6
	v_fmac_f32_e32 v0, v169, v1
	v_max_f32_e32 v1, 0, v14
	v_fmac_f32_e32 v8, v177, v1
	v_max_f32_e32 v1, 0, v7
	v_fmac_f32_e32 v0, v170, v1
	v_max_f32_e32 v1, 0, v15
	v_add_f32_e32 v0, 0, v0
	v_fmac_f32_e32 v8, v178, v1
	v_cndmask_b32_e32 v0, v163, v0, vcc
	v_add_u32_e32 v1, 0xffff0000, v199
	ds_write_b32 v1, v0
	v_add_f32_e32 v0, 0, v8
	v_cmp_le_i32_e32 vcc, v200, v196
	v_add_u32_e32 v1, 0xffff4000, v199
	s_nop 0
	v_cndmask_b32_e32 v0, v163, v0, vcc
	ds_write_b32 v1, v0
	v_mfma_f32_32x32x16_bf16 v[0:15], v[32:35], v[60:63], 0
	v_cmp_le_i32_e32 vcc, v200, v197
	v_mfma_f32_32x32x16_bf16 v[0:15], v[36:39], v[56:59], v[0:15]
	v_mfma_f32_32x32x16_bf16 v[0:15], v[40:43], v[52:55], v[0:15]
	v_mfma_f32_32x32x16_bf16 v[0:15], v[44:47], v[48:51], v[0:15]
	s_nop 11
	v_max_f32_e32 v0, 0, v0
	v_fma_f32 v0, v179, v0, 0
	v_max_f32_e32 v1, 0, v1
	v_max_f32_e32 v8, 0, v8
	v_fmac_f32_e32 v0, v180, v1
	v_fma_f32 v8, v187, v8, 0
	v_max_f32_e32 v1, 0, v9
	v_fmac_f32_e32 v8, v188, v1
	v_max_f32_e32 v1, 0, v2
	v_fmac_f32_e32 v0, v181, v1
	v_max_f32_e32 v1, 0, v10
	v_fmac_f32_e32 v8, v189, v1
	v_max_f32_e32 v1, 0, v3
	v_fmac_f32_e32 v0, v182, v1
	v_max_f32_e32 v1, 0, v11
	v_fmac_f32_e32 v8, v190, v1
	v_max_f32_e32 v1, 0, v4
	v_fmac_f32_e32 v0, v183, v1
	v_max_f32_e32 v1, 0, v12
	v_fmac_f32_e32 v8, v191, v1
	v_max_f32_e32 v1, 0, v5
	v_fmac_f32_e32 v0, v184, v1
	v_max_f32_e32 v1, 0, v13
	v_fmac_f32_e32 v8, v192, v1
	v_max_f32_e32 v1, 0, v6
	v_fmac_f32_e32 v0, v185, v1
	v_max_f32_e32 v1, 0, v14
	v_fmac_f32_e32 v8, v193, v1
	v_max_f32_e32 v1, 0, v7
	v_fmac_f32_e32 v0, v186, v1
	v_max_f32_e32 v1, 0, v15
	v_fmac_f32_e32 v8, v194, v1
	v_add_f32_e32 v0, 0, v0
	v_cndmask_b32_e32 v0, v163, v0, vcc
	v_add_f32_e32 v1, 0, v8
	v_cmp_le_i32_e32 vcc, v200, v198
	v_add_u32_e32 v200, 0x100, v200
	s_nop 0
	v_cndmask_b32_e32 v1, v163, v1, vcc
	ds_write2st64_b32 v199, v0, v1 offset1:64
	v_add_u32_e32 v199, 0x400, v199
	s_add_i32 s98, s7, 8
	s_cmp_ge_u32 s98, s5
	s_cbranch_scc1 .Lidx_w0
	s_waitcnt vmcnt(4)
	s_branch .Lidx_wd

; #define MFMA32(a, b, c) __builtin_amdgcn_mfma_f32_32x32x16_bf16((a), (b), (c), 0, 0, 0)
; DI void index_unit(Frame& F, int b, int t0) {
;     ...
;         for (int kt = w; kt < nkt; kt += NWAVES) {
;             const int s = 32 * kt + r;
;             if (kt + NWAVES < nkt) { const bf16* kp = H0 + (size_t)(b * SEQ + s + 32 * NWAVES) * EVEN_LD + C_KI + 8 * hf;
; #pragma unroll
;                 for (int st = 0; st < 4; ++st) kn[st] = *(const bf16x8*)(kp + 16 * st); }
; #pragma unroll
;             for (int mt = 0; mt < 2; ++mt) {
;                 f32x16 x;
; #pragma unroll
;                 for (int i = 0; i < 16; ++i) x[i] = 0.f;
; #pragma unroll
;                 for (int st = 0; st < 4; ++st) x = MFMA32(qa[mt][st], kb[st], x);
;                 float s0v = 0.f, s1v = 0.f;
; #pragma unroll
;                 for (int i = 0; i < 8; ++i) { s0v += wv[mt][i] * fmaxf(x[i], 0.f); s1v += wv[mt][8 + i] * fmaxf(x[8 + i], 0.f); }
;                 const int tq0 = 4 * mt + 2 * hf;
;                 sc[tq0 * 4096 + s] = (s <= t0 + tq0) ? (s0v + 0.f) : -1e30f;
;                 sc[(tq0 + 1) * 4096 + s] = (s <= t0 + tq0 + 1) ? (s1v + 0.f) : -1e30f;
;             }
; #pragma unroll
;             for (int st = 0; st < 4; ++st) kb[st] = kn[st];
;         }
.Lidx_wd:
	s_cmp_lg_u32 s100, 0
	s_cbranch_scc1 .Lidx_cpX
	v_mov_b64_e32 v[60:61], v[236:237]
	v_mov_b64_e32 v[62:63], v[238:239]
	v_mov_b64_e32 v[56:57], v[232:233]
	v_mov_b64_e32 v[58:59], v[234:235]
	v_mov_b64_e32 v[52:53], v[240:241]
	v_mov_b64_e32 v[54:55], v[242:243]
	v_mov_b64_e32 v[48:49], v[244:245]
	v_mov_b64_e32 v[50:51], v[246:247]
	s_branch .Lidx_cpd
.Lidx_cpX:
	v_mov_b64_e32 v[60:61], v[68:69]
	v_mov_b64_e32 v[62:63], v[70:71]
	v_mov_b64_e32 v[56:57], v[64:65]
	v_mov_b64_e32 v[58:59], v[66:67]
	v_mov_b64_e32 v[52:53], v[72:73]
	v_mov_b64_e32 v[54:55], v[74:75]
	v_mov_b64_e32 v[48:49], v[76:77]
	v_mov_b64_e32 v[50:51], v[78:79]
.Lidx_cpd:
	s_xor_b32 s100, s100, 1
	s_andn2_b64 vcc, exec, s[0:1]
	s_cbranch_vccz .LBB0_216
.LBB0_214:
	s_add_i32 s7, s7, 8
	s_cmp_ge_u32 s7, s5
	s_cselect_b64 s[0:1], -1, 0
	s_add_i32 s98, s7, 8
	s_cmp_ge_u32 s98, s5
	s_cbranch_scc1 .LBB0_213
	v_add_u32_e32 v2, s6, v200
	v_add_u32_e32 v2, 0x100, v2
	v_mov_b64_e32 v[0:1], s[24:25]
	v_mad_i64_i32 v[0:1], s[8:9], v2, s19, v[0:1]
	v_lshl_add_u64 v[0:1], v[0:1], 0, v[80:81]
	v_lshl_add_u64 v[2:3], v[0:1], 0, s[10:11]
	v_add_co_u32_e32 v0, vcc, 0x3000, v0
	s_nop 1
	v_addc_co_u32_e32 v1, vcc, 0, v1, vcc
	s_cmp_lg_u32 s100, 0
	s_cbranch_scc1 .Lidx_ldY
	global_load_dwordx4 v[64:67], v[2:3], off offset:32
	global_load_dwordx4 v[72:75], v[2:3], off offset:64
	global_load_dwordx4 v[68:71], v[0:1], off offset:1024
	global_load_dwordx4 v[76:79], v[2:3], off offset:96
	s_branch .LBB0_213
.Lidx_ldY:
	global_load_dwordx4 v[232:235], v[2:3], off offset:32
	global_load_dwordx4 v[240:243], v[2:3], off offset:64
	global_load_dwordx4 v[236:239], v[0:1], off offset:1024
	global_load_dwordx4 v[244:247], v[2:3], off offset:96
	s_branch .LBB0_213
